# task-start barrier sinking: step-0 K/V global loads of diff and ret mixer tasks issued before the task-start s_barrier (on top of v34)
# baseline (speedup 1.0000x reference)
; #define RT_COMMIT(KR, VR, buf) do { LAS unsigned char* bb_ = lds + (buf) * MX_BUF; \
;         if (kcopy) *(LAS u32x4*)(bb_ + krow * KP + kch * 16) = KR; *(LAS u32x4*)(bb_ + MX_KBYTES + vr * VP + vc * 16) = VR; } while (0)
; __device__ __forceinline__ void wg_ret_task(ParamsCP pp, int layer, LAS unsigned char* lds, int b, int h, int qb, int tid_in) {
;     ...
;     const float lgf = log1pf(-exp2f(-pp->in[4][layer * 8 + h])) * LOG2E, lgb = log1pf(-exp2f(-pp->in[5][layer * 8 + h])) * LOG2E;
;     const int tqA = 16 * jA + c16, tqB = 16 * jB + c16;
;     bf16x8 qA[2], qB[2];
;     { const bf16_t* qp = PROJ + (size_t)(qrowA + c16) * PP + qcol + 8 * quad; qA[0] = *(const bf16x8*)qp; qA[1] = *(const bf16x8*)(qp + 32);
;       const bf16_t* qp2 = PROJ + (size_t)(qrowB + c16) * PP + qcol + 8 * quad; qB[0] = *(const bf16x8*)qp2; qB[1] = *(const bf16x8*)(qp2 + 32); }
;     f32x4 accA[8], accB[8];
; #pragma unroll
;     for (int e0 = 0; e0 < 8; ++e0) { accA[e0] = (f32x4){0.f, 0.f, 0.f, 0.f}; accB[e0] = (f32x4){0.f, 0.f, 0.f, 0.f}; }
;     u32x4 kr0s = (u32x4){0u, 0u, 0u, 0u}, vr0s = kr0s, kr1s = kr0s, vr1s = kr0s;
;     ...
;     __syncthreads();
;     RT_ISSUE(kr0s, vr0s, 0); RT_COMMIT(kr0s, vr0s, 0); RT_ISSUE(kr1s, vr1s, 1);
.Lmx_r_noat:
	s_mov_b64 exec, s[4:5]
	s_load_dwordx4 s[8:11], s[0:1], 0x20
	s_add_i32 s12, s35, s48
	s_lshl_b32 s4, s48, 6
	s_ashr_i32 s13, s12, 31
	s_ashr_i32 s5, s4, 31
	s_lshl_b64 s[12:13], s[12:13], 2
	s_lshl_b64 s[38:39], s[4:5], 1
	s_waitcnt lgkmcnt(0)
	s_add_u32 s8, s8, s12
	s_addc_u32 s9, s9, s13
	global_load_dword v0, v1, s[8:9]
	s_add_u32 s10, s10, s12
	s_addc_u32 s11, s11, s13
	global_load_dword v21, v1, s[10:11]
	s_mov_b32 s15, 0x42fc0000
	v_and_b32_e32 v122, 15, v24
	v_add_u32_e32 v2, s41, v122
	v_add_u32_e32 v4, s40, v122
	v_ashrrev_i32_e32 v3, 31, v2
	v_ashrrev_i32_e32 v5, 31, v4
	v_lshlrev_b64 v[2:3], 12, v[2:3]
	v_lshlrev_b64 v[4:5], 12, v[4:5]
	v_bfe_u32 v32, v24, 4, 2
	v_lshl_add_u64 v[2:3], s[84:85], 0, v[2:3]
	v_lshl_add_u64 v[4:5], s[84:85], 0, v[4:5]
	v_mov_b32_e32 v29, v1
	v_lshlrev_b32_e32 v28, 4, v32
	v_and_b32_e32 v30, 7, v24
	v_bfe_u32 v123, v24, 3, 5
	v_lshlrev_b32_e32 v116, 4, v30
	v_lshl_add_u64 v[2:3], v[2:3], 0, s[38:39]
	v_lshl_add_u64 v[4:5], v[4:5], 0, s[38:39]
	v_lshl_add_u64 v[2:3], v[2:3], 0, v[28:29]
	v_lshl_add_u64 v[16:17], v[4:5], 0, v[28:29]
	global_load_dwordx4 v[4:7], v[2:3], off
	global_load_dwordx4 v[8:11], v[2:3], off offset:64
	global_load_dwordx4 v[12:15], v[16:17], off
	s_nop 0
	global_load_dwordx4 v[16:19], v[16:17], off offset:64
	s_waitcnt vmcnt(5)
	v_cmp_lt_f32_e32 vcc, s15, v0
	s_and_b64 s[8:9], vcc, exec
	s_cselect_b32 s14, 0xffffffc0, 0
	v_cndmask_b32_e32 v20, 0, v240, vcc
	v_sub_f32_e32 v0, v20, v0
	v_exp_f32_e32 v0, v0
	s_waitcnt vmcnt(4)
	v_cmp_lt_f32_e32 vcc, s15, v21
	s_and_b64 s[8:9], vcc, exec
	s_cselect_b32 s10, 0xffffffc0, 0
	v_cndmask_b32_e32 v22, 0, v240, vcc
	v_ldexp_f32 v33, v0, s14
	v_sub_f32_e32 v0, v22, v21
	v_exp_f32_e32 v0, v0
	v_sub_f32_e32 v35, 1.0, v33
	v_frexp_mant_f32_e32 v2, v35
	s_mov_b32 s8, 0x3f2aaaab
	v_ldexp_f32 v29, v0, s10
	v_sub_f32_e32 v34, 1.0, v29
	v_frexp_mant_f32_e32 v0, v34
	v_cmp_gt_f32_e64 s[12:13], s8, v2
	v_cmp_gt_f32_e32 vcc, s8, v0
	s_movk_i32 s8, 0xff
	v_mov_b32_e32 v2, v1
	v_mov_b32_e32 v3, v1
	v_cmp_lt_i32_e64 s[14:15], s8, v24
	s_movk_i32 s8, 0x100
	v_mov_b32_e32 v0, v1
	v_mov_b64_e32 v[22:23], v[2:3]
	v_cmp_gt_i32_e64 s[8:9], s8, v24
	v_mov_b64_e32 v[20:21], v[0:1]
	s_and_saveexec_b64 s[38:39], s[8:9]
	s_cbranch_execz .LBB0_397
	v_mov_b32_e32 v0, s49
	v_mov_b32_e32 v2, s76
	v_cmp_gt_u32_e64 s[10:11], 16, v123
	v_mov_b32_e32 v117, v1
	s_nop 0
	v_cndmask_b32_e64 v0, v0, v2, s[10:11]
	v_add_lshl_u32 v0, v0, v123, 12
	v_lshl_add_u64 v[2:3], s[84:85], 0, v[0:1]
	v_lshl_add_u64 v[2:3], s[4:5], 1, v[2:3]
	v_lshl_add_u64 v[2:3], v[2:3], 0, v[116:117]
	global_load_dwordx4 v[20:23], v[2:3], off offset:1024
.LBB0_397:
	s_or_b64 exec, exec, s[38:39]
	v_ashrrev_i32_e32 v3, 2, v24
	s_lshl_b32 s48, s48, 7
	v_add_u32_e32 v0, s48, v3
	v_mov_b64_e32 v[26:27], s[16:17]
	s_mov_b32 s10, 0x10200
	v_and_b32_e32 v2, 3, v24
	s_or_b32 s38, s64, 0x100
	v_mad_i64_i32 v[118:119], s[10:11], v0, s10, v[26:27]
	v_mov_b32_e32 v0, s38
	v_mov_b32_e32 v25, s76
	v_cmp_gt_u32_e64 s[10:11], 2, v2
	v_lshlrev_b32_e32 v24, 3, v24
	v_and_b32_e32 v124, 8, v24
	v_cndmask_b32_e64 v0, v0, v25, s[10:11]
	v_or_b32_e32 v0, v0, v124
	v_lshl_add_u64 v[24:25], v[0:1], 1, v[118:119]
	global_load_dwordx4 v[24:27], v[24:25], off
	s_barrier
	s_and_saveexec_b64 s[38:39], s[8:9]
	s_cbranch_execz .LBB0_399
	v_mul_u32_u24_e32 v0, 0x90, v123
	v_add3_u32 v0, 0, v0, v116
	s_waitcnt vmcnt(1)
	ds_write_b128 v0, v[20:23]

; #define DF_COMMIT(buf) do { LAS unsigned char* bb_ = lds + (buf) * DF_BUF; \
;         _Pragma("unroll") for (int i_ = 0; i_ < 2; ++i_) { const int id_ = tid + 512 * i_, kr_ = id_ >> 5, kc_ = id_ & 31, vr_ = id_ >> 2, vc_ = id_ & 3; \
;             *(LAS u32x4*)(bb_ + kr_ * DF_KP + kc_ * 16) = kreg[i_]; *(LAS u32x4*)(bb_ + DF_KBYTES + vr_ * VP + vc_ * 16) = vreg[i_]; } } while (0)
; __device__ __forceinline__ void wg_diff_task(ParamsCP pp, int layer, LAS unsigned char* lds, int b, int h, int qb, int tid_in) {
;     ...
;     { const bf16_t* qp = PROJ + (size_t)(qrow0 + c16) * PP + qcol + 8 * quad;
; #pragma unroll
;         for (int ks = 0; ks < 4; ++ks) { qf0[ks] = *(const bf16x8*)(qp + 32 * ks); qf1[ks] = *(const bf16x8*)(qp + 128 + 32 * ks); } }
;     f32x4 acc0[16], acc1[16];
; #pragma unroll
;     for (int e0 = 0; e0 < 16; ++e0) { acc0[e0] = (f32x4){0.f, 0.f, 0.f, 0.f}; acc1[e0] = (f32x4){0.f, 0.f, 0.f, 0.f}; }
;     float ls0 = 0.f, ls1 = 0.f;
;     u32x4 kreg[2], vreg[2];
;     ...
;     __syncthreads();
;     DF_ISSUE(0); DF_COMMIT(0);
;     __syncthreads();
.Lmx_d_noat:
	s_mov_b64 exec, s[4:5]
	v_and_b32_e32 v207, 15, v2
	v_add_u32_e32 v4, s30, v207
	s_lshl_b32 s24, s10, 8
	v_ashrrev_i32_e32 v5, 31, v4
	s_ashr_i32 s25, s24, 31
	v_lshlrev_b64 v[4:5], 12, v[4:5]
	v_bfe_u32 v208, v2, 4, 2
	v_lshl_add_u64 v[4:5], s[84:85], 0, v[4:5]
	s_lshl_b64 s[4:5], s[24:25], 1
	v_lshl_add_u64 v[4:5], v[4:5], 0, s[4:5]
	v_lshlrev_b32_e32 v0, 4, v208
	v_lshl_add_u64 v[4:5], v[4:5], 0, v[0:1]
	s_mov_b64 s[10:11], 0x8100000
	s_add_i32 s38, s24, 0x400
	v_lshl_add_u64 v[6:7], v[4:5], 0, s[10:11]
	s_mov_b32 s10, 0x8100000
	s_bitset1_b32 s9, 8
	v_add_co_u32_e32 v4, vcc, s10, v4
	s_add_u32 s4, s84, s4
	v_lshlrev_b32_e32 v10, 4, v2
	v_addc_co_u32_e32 v5, vcc, 0, v5, vcc
	s_addc_u32 s5, s85, s5
	v_and_b32_e32 v180, 0x1f0, v10
	v_mov_b32_e32 v181, v1
	global_load_dwordx4 v[114:117], v[4:5], off
	global_load_dwordx2 v[178:179], v1, s[20:21]
	global_load_dwordx4 v[118:121], v[6:7], off offset:64
	global_load_dwordx4 v[122:125], v[6:7], off offset:256
	global_load_dwordx4 v[126:129], v[6:7], off offset:320
	global_load_dwordx4 v[134:137], v[6:7], off offset:128
	global_load_dwordx4 v[138:141], v[6:7], off offset:192
	global_load_dwordx4 v[142:145], v[6:7], off offset:384
	global_load_dwordx4 v[146:149], v[6:7], off offset:448
	v_and_b32_e32 v3, 2, v2
	v_lshl_add_u64 v[4:5], s[4:5], 0, v[180:181]
	s_mov_b64 s[4:5], 0x8100800
	v_lshlrev_b32_e32 v6, 3, v2
	v_lshl_add_u64 v[182:183], v[4:5], 0, s[4:5]
	v_mov_b32_e32 v4, s9
	v_mov_b32_e32 v11, s8
	v_cmp_eq_u32_e64 s[8:9], 0, v3
	v_and_b32_e32 v181, 8, v6
	v_ashrrev_i32_e32 v209, 5, v2
	v_cndmask_b32_e64 v3, v4, v11, s[8:9]
	v_or_b32_e32 v4, v3, v181
	v_mov_b32_e32 v3, s37
	v_cmp_gt_i32_e64 s[10:11], 16, v209
	v_ashrrev_i32_e32 v12, 2, v2
	v_add_u32_e32 v2, 0x200, v2
	v_cndmask_b32_e64 v6, v3, v11, s[10:11]
	v_add_u32_e32 v6, v6, v209
	v_ashrrev_i32_e32 v7, 31, v6
	v_ashrrev_i32_e32 v5, 31, v4
	v_lshlrev_b64 v[6:7], 12, v[6:7]
	v_ashrrev_i32_e32 v210, 5, v2
	v_lshl_add_u64 v[4:5], v[4:5], 1, s[16:17]
	v_lshl_add_u64 v[6:7], v[182:183], 0, v[6:7]
	v_add_u32_e32 v13, s38, v12
	s_mov_b32 s41, 0x10200
	v_cmp_gt_i32_e64 s[12:13], 16, v210
	s_waitcnt vmcnt(63) expcnt(7) lgkmcnt(15)
	v_mad_i64_i32 v[8:9], s[4:5], v13, s41, v[4:5]
	global_load_dwordx4 v[162:165], v[6:7], off
	global_load_dwordx4 v[166:169], v[8:9], off
	v_ashrrev_i32_e32 v6, 2, v2
	v_cndmask_b32_e64 v2, v3, v11, s[12:13]
	v_add_u32_e32 v2, v2, v210
	v_ashrrev_i32_e32 v3, 31, v2
	v_lshlrev_b64 v[2:3], 12, v[2:3]
	v_lshl_add_u64 v[2:3], v[182:183], 0, v[2:3]
	v_add_u32_e32 v7, s38, v6
	global_load_dwordx4 v[170:173], v[2:3], off
	v_mad_i64_i32 v[2:3], s[4:5], v7, s41, v[4:5]
	global_load_dwordx4 v[174:177], v[2:3], off
	s_barrier
	v_mad_i64_i32 v[184:185], s[4:5], v13, s41, 0
	v_mad_i64_i32 v[186:187], s[4:5], v7, s41, 0
	v_mov_b32_e32 v2, 0x3fb8aa3b
	s_movk_i32 s5, 0x210
	v_and_b32_e32 v212, 48, v10
	v_mul_lo_u32 v213, v209, s5
	s_movk_i32 s4, 0x50
	v_add_u32_e32 v3, 0, v212
	v_mul_lo_u32 v214, v12, s4
	v_mul_lo_u32 v215, v210, s5
	v_mul_lo_u32 v216, v6, s4
	v_mov_b32_e32 v22, 0
	s_mov_b32 s38, 3
	s_mov_b32 s39, 0
	v_lshlrev_b32_e32 v211, 3, v208
	v_mul_u32_u24_e32 v217, 0x210, v207
	v_mul_u32_u24_e32 v218, 0x50, v207
	v_mov_b32_e32 v23, v22
	v_mov_b32_e32 v24, v22
	v_mov_b32_e32 v25, v22
	v_mov_b32_e32 v50, v22
	v_mov_b32_e32 v51, v22
	v_mov_b32_e32 v52, v22
	v_mov_b32_e32 v53, v22
	v_mov_b32_e32 v58, v22
	v_mov_b32_e32 v59, v22
	s_waitcnt vmcnt(11)
	v_readfirstlane_b32 s40, v179
	v_mov_b32_e32 v60, v22
	v_mov_b32_e32 v61, v22
	v_mul_f32_e32 v179, s40, v2
	v_add_u32_e32 v2, 0, v180
	v_add_u32_e32 v4, v2, v213
	v_add_u32_e32 v2, v2, v215
	s_add_i32 s40, s37, 32
	v_mov_b32_e32 v70, v22
	v_mov_b32_e32 v71, v22
	v_mov_b32_e32 v72, v22
	v_mov_b32_e32 v73, v22
	v_mov_b32_e32 v82, v22
	v_mov_b32_e32 v83, v22
	v_mov_b32_e32 v84, v22
	v_mov_b32_e32 v85, v22
	v_mov_b32_e32 v90, v22
	v_mov_b32_e32 v91, v22
	v_mov_b32_e32 v92, v22
	v_mov_b32_e32 v93, v22
	v_mov_b32_e32 v102, v22
	v_mov_b32_e32 v103, v22
	v_mov_b32_e32 v104, v22
	v_mov_b32_e32 v105, v22
	v_mov_b32_e32 v130, v22
	v_mov_b32_e32 v131, v22
	v_mov_b32_e32 v132, v22
	v_mov_b32_e32 v133, v22
	v_mov_b32_e32 v42, v22
	v_mov_b32_e32 v43, v22
	v_mov_b32_e32 v44, v22
	v_mov_b32_e32 v45, v22
	v_mov_b32_e32 v34, v22
	v_mov_b32_e32 v35, v22
	v_mov_b32_e32 v36, v22
	v_mov_b32_e32 v37, v22
	v_mov_b32_e32 v26, v22
	v_mov_b32_e32 v27, v22
	v_mov_b32_e32 v28, v22
	s_waitcnt vmcnt(3)
	ds_write_b128 v4, v[162:165]
	v_add_u32_e32 v4, v3, v214
	s_waitcnt vmcnt(2)
	ds_write_b128 v4, v[166:169] offset:16896
	v_mov_b32_e32 v29, v22
	v_mov_b32_e32 v18, v22
	v_mov_b32_e32 v19, v22
	v_mov_b32_e32 v20, v22
	v_mov_b32_e32 v21, v22
	v_mov_b32_e32 v14, v22
	s_waitcnt vmcnt(1)
	ds_write_b128 v2, v[170:173]
	v_add_u32_e32 v2, v3, v216
	v_mov_b32_e32 v15, v22
	s_waitcnt vmcnt(0)
	ds_write_b128 v2, v[174:177] offset:16896
	v_mov_b32_e32 v16, v22
	v_mov_b32_e32 v17, v22
	v_mov_b32_e32 v10, v22
	v_mov_b32_e32 v11, v22
	v_mov_b32_e32 v12, v22
	v_mov_b32_e32 v13, v22
	v_mov_b32_e32 v6, v22
	v_mov_b32_e32 v7, v22
	v_mov_b32_e32 v8, v22
	v_mov_b32_e32 v9, v22
	v_mov_b32_e32 v2, v22
	v_mov_b32_e32 v3, v22
	v_mov_b32_e32 v4, v22
	v_mov_b32_e32 v5, v22
	v_mov_b32_e32 v158, v22
	v_mov_b32_e32 v159, v22
	v_mov_b32_e32 v160, v22
	v_mov_b32_e32 v161, v22
	v_mov_b32_e32 v154, v22
	v_mov_b32_e32 v155, v22
	v_mov_b32_e32 v156, v22
	v_mov_b32_e32 v157, v22
	v_mov_b32_e32 v150, v22
	v_mov_b32_e32 v151, v22
	v_mov_b32_e32 v152, v22
	v_mov_b32_e32 v153, v22
	v_mov_b32_e32 v110, v22
	v_mov_b32_e32 v111, v22
	v_mov_b32_e32 v112, v22
	v_mov_b32_e32 v113, v22
	v_mov_b32_e32 v106, v22
	v_mov_b32_e32 v107, v22
	v_mov_b32_e32 v108, v22
	v_mov_b32_e32 v109, v22
	v_mov_b32_e32 v98, v22
	v_mov_b32_e32 v99, v22
	v_mov_b32_e32 v100, v22
	v_mov_b32_e32 v101, v22
	v_mov_b32_e32 v94, v22
	v_mov_b32_e32 v95, v22
	v_mov_b32_e32 v96, v22
	v_mov_b32_e32 v97, v22
	v_mov_b32_e32 v86, v22
	v_mov_b32_e32 v87, v22
	v_mov_b32_e32 v88, v22
	v_mov_b32_e32 v89, v22
	v_mov_b32_e32 v78, v22
	v_mov_b32_e32 v79, v22
	v_mov_b32_e32 v80, v22
	v_mov_b32_e32 v81, v22
	v_mov_b32_e32 v74, v22
	v_mov_b32_e32 v75, v22
	v_mov_b32_e32 v76, v22
	v_mov_b32_e32 v77, v22
	v_mov_b32_e32 v66, v22
	v_mov_b32_e32 v67, v22
	v_mov_b32_e32 v68, v22
	v_mov_b32_e32 v69, v22
	v_mov_b32_e32 v62, v22
	v_mov_b32_e32 v63, v22
	v_mov_b32_e32 v64, v22
	v_mov_b32_e32 v65, v22
	v_mov_b32_e32 v54, v22
	v_mov_b32_e32 v55, v22
	v_mov_b32_e32 v56, v22
	v_mov_b32_e32 v57, v22
	v_mov_b32_e32 v46, v22
	v_mov_b32_e32 v47, v22
	v_mov_b32_e32 v48, v22
	v_mov_b32_e32 v49, v22
	v_mov_b32_e32 v38, v22
	v_mov_b32_e32 v39, v22
	v_mov_b32_e32 v40, v22
	v_mov_b32_e32 v41, v22
	v_mov_b32_e32 v30, v22
	v_mov_b32_e32 v31, v22
	v_mov_b32_e32 v32, v22
	v_mov_b32_e32 v33, v22
	v_mov_b32_e32 v188, v22
	v_mov_b32_e32 v189, v22
	v_readfirstlane_b32 s4, v206
	s_nop 3
	s_bitcmp1_b32 s4, 8
	s_cbranch_scc0 .Lprio_d_skip
	s_setprio 1
